# in-proj: stagger WG groups (blockIdx>>6) by ~2us each at phase start so epilogue store bursts do not coincide
# speedup vs baseline: 1.0229x; 1.0005x over previous
.LBB0_447:
	s_andn2_b64 vcc, exec, s[0:1]
	s_cbranch_vccnz .LBB0_584
	s_mov_b64 s[4:5], s[40:41]
	s_mov_b64 s[6:7], s[40:41]
	s_mov_b64 s[36:37], s[40:41]
	s_mov_b64 s[38:39], s[40:41]
	s_mov_b64 s[0:1], s[40:41]
	s_mov_b32 s26, -1
	s_nop 0
	v_mbcnt_lo_u32_b32 v0, s26, 0
	v_mbcnt_hi_u32_b32 v0, s26, v0
	v_readlane_b32 s26, v252, 5
	s_nop 1
	v_add_u32_e32 v8, s26, v0
	v_readlane_b32 s26, v252, 9
	v_readlane_b32 s27, v252, 10
	s_andn2_b64 vcc, exec, s[26:27]
	v_readfirstlane_b32 s26, v8
	s_cbranch_vccnz .LBB0_528
	v_readlane_b32 s28, v252, 0
	s_nop 1
	s_lshr_b32 s28, s28, 6
	s_cmp_eq_u32 s28, 0
	s_cbranch_scc1 .LstagA_done
.LstagA_loop:
	s_sleep 64
	s_sub_u32 s28, s28, 1
	s_cmp_lg_u32 s28, 0
	s_cbranch_scc1 .LstagA_loop
.LstagA_done:
	v_lshlrev_b32_e32 v0, 4, v8
	s_waitcnt lgkmcnt(0)
	v_add_u32_e32 v1, 0x2000, v0
	v_ashrrev_i32_e32 v2, 31, v1
	v_lshrrev_b32_e32 v2, 22, v2
	v_add_u32_e32 v2, v1, v2
	v_ashrrev_i32_e32 v9, 10, v2
	v_mul_i32_i24_e32 v2, 0x400, v9
	v_sub_u32_e32 v1, v1, v2
	v_lshrrev_b32_e32 v2, 4, v1
	v_bitop3_b32 v1, v2, v1, 32 bitop3:0x6c
	v_readlane_b32 s28, v254, 43
	v_ashrrev_i32_e32 v2, 31, v1
	v_readlane_b32 s29, v254, 44
	s_add_u32 s58, s4, 0x13600000
	v_lshrrev_b32_e32 v2, 26, v2
	s_addc_u32 s59, s5, 0
	s_mov_b32 s5, s29
	v_add_u32_e32 v2, v1, v2
	v_lshlrev_b32_e32 v3, 3, v9
	s_mul_i32 s28, s96, 0x2c0000
	v_writelane_b32 v254, s4, 43
	v_ashrrev_i32_e32 v10, 6, v2
	v_and_b32_e32 v3, -16, v3
	v_writelane_b32 v254, s5, 44
	s_lshl_b64 s[4:5], s[28:29], 1
	v_add_u32_e32 v3, v10, v3
	s_add_u32 s34, s6, s4
	v_and_b32_e32 v4, 3, v10
	s_mov_b32 s4, 0x1fffe0
	v_lshrrev_b32_e32 v5, 2, v3
	v_lshlrev_b32_e32 v6, 1, v3
	v_and_or_b32 v4, v3, s4, v4
	v_and_b32_e32 v5, 4, v5
	v_and_b32_e32 v6, 24, v6
	v_and_b32_e32 v2, 0xc0, v2
	v_or3_b32 v4, v4, v5, v6
	v_sub_u32_e32 v1, v1, v2
	v_mov_b32_e32 v6, 1
	v_lshlrev_b32_e32 v5, 5, v9
	v_ashrrev_i16_sdwa v1, v6, sext(v1) dst_sel:DWORD dst_unused:UNUSED_PAD src0_sel:DWORD src1_sel:BYTE_0
	v_and_b32_e32 v5, 32, v5
	v_bfe_i32 v11, v1, 0, 16
	v_add_lshl_u32 v1, v5, v11, 1
	v_lshl_add_u32 v130, v4, 11, v1
	v_lshl_add_u32 v132, v3, 11, v1
	v_bfe_i32 v1, v8, 27, 1
	v_lshrrev_b32_e32 v1, 22, v1
	v_add_u32_e32 v1, v0, v1
	v_and_b32_e32 v1, 0xfffffc00, v1
	v_sub_u32_e32 v0, v0, v1
	v_lshrrev_b32_e32 v1, 4, v0
	v_ashrrev_i32_e32 v2, 31, v8
	v_bitop3_b32 v0, v1, v0, 32 bitop3:0x6c
	v_lshrrev_b32_e32 v2, 26, v2
	v_ashrrev_i32_e32 v1, 31, v0
	v_add_u32_e32 v2, v8, v2
	v_lshrrev_b32_e32 v1, 26, v1
	v_ashrrev_i32_e32 v13, 6, v2
	v_add_u32_e32 v1, v0, v1
	v_lshlrev_b32_e32 v2, 3, v13
	v_ashrrev_i32_e32 v12, 6, v1
	v_and_b32_e32 v2, -16, v2
	v_add_u32_e32 v2, v12, v2
	v_and_b32_e32 v3, 3, v12
	v_lshrrev_b32_e32 v4, 2, v2
	v_lshlrev_b32_e32 v5, 1, v2
	v_and_b32_e32 v1, 0xc0, v1
	s_addc_u32 s60, s7, s5
	s_ashr_i32 s28, s26, 6
	v_and_or_b32 v3, v2, s4, v3
	v_and_b32_e32 v4, 4, v4
	v_and_b32_e32 v5, 24, v5
	v_sub_u32_e32 v0, v0, v1
	s_ashr_i32 s27, s26, 8
	s_lshl_b32 s61, s28, 10
	v_or3_b32 v3, v3, v4, v5
	v_lshlrev_b32_e32 v4, 5, v13
	v_ashrrev_i16_sdwa v0, v6, sext(v0) dst_sel:DWORD dst_unused:UNUSED_PAD src0_sel:DWORD src1_sel:BYTE_0
	v_readlane_b32 s4, v253, 46
	v_and_b32_e32 v4, 32, v4
	v_bfe_i32 v14, v0, 0, 16
	v_readlane_b32 s5, v253, 47
	s_add_u32 s4, s34, s4
	v_add_lshl_u32 v0, v4, v14, 1
	s_addc_u32 s5, s60, s5
	s_add_i32 s62, s61, 0
	v_lshl_add_u32 v64, v3, 11, v0
	s_add_i32 m0, s62, 0x10000
	v_lshl_add_u32 v134, v2, 11, v0
	global_load_lds_dwordx4 v64, s[4:5]
	s_add_i32 m0, s62, 0x12000
	s_add_u32 s6, s4, 0x40000
	global_load_lds_dwordx4 v130, s[4:5]
	s_addc_u32 s7, s5, 0
	s_add_i32 m0, s62, 0x14000
	v_mov_b32_e32 v131, v65
	global_load_lds_dwordx4 v64, s[6:7]
	s_add_i32 m0, s62, 0x16000
	v_mov_b32_e32 v135, v65
	global_load_lds_dwordx4 v130, s[6:7]
	v_readlane_b32 s6, v253, 57
	v_readlane_b32 s7, v253, 58
	s_add_u32 s30, s58, s6
	s_addc_u32 s31, s59, s7
	s_add_i32 s63, s62, 0x2000
	s_mov_b32 m0, s62
	s_add_u32 s6, s30, 0x40000
	global_load_lds_dwordx4 v134, s[30:31]
	s_mov_b32 m0, s63
	s_addc_u32 s7, s31, 0
	s_add_i32 s64, s62, 0x4000
	global_load_lds_dwordx4 v132, s[30:31]
	s_mov_b32 m0, s64
	s_add_i32 s65, s62, 0x6000
	global_load_lds_dwordx4 v134, s[6:7]
	s_mov_b32 m0, s65
	v_mov_b32_e32 v133, v65
	global_load_lds_dwordx4 v132, s[6:7]
	s_cmp_eq_u32 s27, 1
	v_lshl_add_u64 v[6:7], s[4:5], 0, v[64:65]
	v_lshl_add_u64 v[4:5], s[4:5], 0, v[130:131]
	v_lshl_add_u64 v[0:1], s[30:31], 0, v[134:135]
	s_cselect_b64 s[6:7], -1, 0
	s_cmp_lg_u32 s27, 1
	v_lshl_add_u64 v[2:3], s[30:31], 0, v[132:133]
	s_cbranch_scc1 .LBB0_451
	s_barrier
